# Strategy 6 LDS bank conflicts: ssm1 u staging rows padded to 272 B so the f32-MFMA A-operand column reads (32 rows, same column) are 2-way instead of 32-way conflicted
# speedup vs baseline: 1.0423x; 1.0019x over previous
; DI int tidx() { int t = threadIdx.x & 255; asm volatile("" : "+v"(t)); return t; }
; DI void ssm_stage_u(PREF p, int b, int c, int gq, float* uS) {
;   const int tid = tidx();
;   int row = tid >> 2, cc = (tid & 3) * 16;
;   const u16* src = p.hb + (size_t)(b * S_ + c * 64 + row) * HW + OFF_U + gq * 64 + cc;
;   float f[16];
;   unpack8(*(const u32x4*)src, f); unpack8(*(const u32x4*)(src + 8), f + 8);
; #pragma unroll
;   for (int j = 0; j < 4; ++j) *(float4*)(uS + row * 64 + cc + 4 * j) = make_float4(f[4 * j], f[4 * j + 1], f[4 * j + 2], f[4 * j + 3]);
; }
; DI void ssm1_item(PREF p, int l, int item, unsigned char* ldsb) {
;   const int gq = item & 3, c = (item >> 2) & 63, b = item >> 8;
;   const int tid = tidx(), w = tid >> 6, lane = tid & 63;
;   const int g = gq * 4 + w;
;   float* uS = (float*)ldsb;
;   __syncthreads();
;   ssm_stage_u(p, b, c, gq, uS);
;   __syncthreads();
;   const size_t pi = (size_t)(l * 16 + g) * 64 + lane;
;   float bre[16], bim[16];
; #pragma unroll
;   for (int j = 0; j < 16; ++j) { bre[j] = p.bbre[pi * 16 + j]; bim[j] = p.bbim[pi * 16 + j]; }
;   const float lr = p.lam[pi * 2], li = p.lam[pi * 2 + 1];
.LBB0_422:
	s_ashr_i32 s14, s12, 8
	v_mov_b32_e32 v25, v169
	v_mov_b32_e32 v0, v169
	s_lshl_b32 s1, s12, 4
	s_waitcnt lgkmcnt(0)
	s_barrier
	s_lshl_b32 s0, s14, 12
	s_and_b32 s15, s1, 0xfc0
	v_ashrrev_i32_e32 v10, 2, v0
	v_lshlrev_b32_e32 v0, 4, v0
	s_or_b32 s0, s15, s0
	v_and_b32_e32 v11, 48, v0
	v_add_u32_e32 v0, s0, v10
	s_load_dwordx2 s[0:1], s[18:19], 0x140
	s_and_b32 s16, s12, 3
	s_lshl_b32 s52, s16, 7
	v_ashrrev_i32_e32 v12, 6, v25
	v_lshl_add_u32 v41, s16, 2, v12
	s_waitcnt lgkmcnt(0)
	v_mov_b64_e32 v[2:3], s[0:1]
	v_mad_i64_i32 v[2:3], s[0:1], v0, s60, v[2:3]
	v_lshl_add_u64 v[2:3], v[2:3], 0, s[52:53]
	v_lshlrev_b32_e32 v0, 1, v11
	v_lshl_add_u64 v[6:7], v[2:3], 0, v[0:1]
	global_load_dwordx4 v[2:5], v[6:7], off offset:2880
	s_nop 0
	global_load_dwordx4 v[6:9], v[6:7], off offset:2896
	v_mul_u32_u24_e32 v12, 0x110, v10
	v_lshlrev_b32_e32 v11, 2, v11
	v_add_u32_e32 v10, s13, v41
	s_load_dwordx2 s[0:1], s[18:19], 0x118
	v_add3_u32 v24, s33, v12, v11
	v_ashrrev_i32_e32 v11, 31, v10
	v_and_b32_e32 v0, 63, v25
	v_lshlrev_b64 v[22:23], 6, v[10:11]
	v_or_b32_e32 v22, v22, v0
	v_lshlrev_b64 v[10:11], 6, v[22:23]
	v_lshl_add_u64 v[18:19], s[10:11], 0, v[10:11]
	s_waitcnt lgkmcnt(0)
	v_lshl_add_u64 v[20:21], s[0:1], 0, v[10:11]
	v_lshl_add_u64 v[22:23], v[22:23], 3, s[8:9]
	v_and_b32_e32 v25, 0xffffffc0, v25
	s_mov_b32 s16, 0
	v_add_u32_e32 v42, s33, v25
	v_mov_b32_e32 v40, 0
	s_waitcnt vmcnt(1)
	v_lshlrev_b32_e32 v10, 16, v2
	v_and_b32_e32 v11, 0xffff0000, v2
	v_lshlrev_b32_e32 v12, 16, v3
	v_and_b32_e32 v13, 0xffff0000, v3
	v_lshlrev_b32_e32 v2, 16, v4
	v_and_b32_e32 v3, 0xffff0000, v4
	v_lshlrev_b32_e32 v4, 16, v5
	v_and_b32_e32 v5, 0xffff0000, v5
	s_waitcnt vmcnt(0)
	v_lshlrev_b32_e32 v14, 16, v6
	v_and_b32_e32 v15, 0xffff0000, v6
	v_lshlrev_b32_e32 v16, 16, v7
	v_and_b32_e32 v17, 0xffff0000, v7
	v_lshlrev_b32_e32 v6, 16, v8
	v_and_b32_e32 v7, 0xffff0000, v8
	v_lshlrev_b32_e32 v8, 16, v9
	v_and_b32_e32 v9, 0xffff0000, v9
	ds_write_b128 v24, v[10:13]
	ds_write_b128 v24, v[2:5] offset:16
	ds_write_b128 v24, v[14:17] offset:32
	ds_write_b128 v24, v[6:9] offset:48
	s_waitcnt lgkmcnt(0)
	s_barrier
	global_load_dwordx4 v[2:5], v[18:19], off offset:16
	global_load_dwordx4 v[6:9], v[20:21], off offset:16
	global_load_dwordx4 v[30:33], v[18:19], off offset:32
	global_load_dwordx4 v[10:13], v[20:21], off offset:32
	global_load_dwordx4 v[34:37], v[18:19], off offset:48
	global_load_dwordx4 v[14:17], v[20:21], off offset:48
	global_load_dwordx4 v[44:47], v[18:19], off
	s_nop 0
	global_load_dwordx4 v[18:21], v[20:21], off
	v_mov_b32_e32 v24, 0
	global_load_dwordx2 v[22:23], v[22:23], off
	s_waitcnt vmcnt(8)
	v_mov_b32_e32 v26, v5
	s_waitcnt vmcnt(7)
	v_mov_b32_e32 v27, v9
	s_waitcnt vmcnt(6)
	v_mov_b32_e32 v28, v30
	s_waitcnt vmcnt(5)
	v_mov_b32_e32 v29, v10
	v_mov_b32_e32 v10, v31
	v_mov_b32_e32 v30, v32
	v_mov_b32_e32 v31, v12
	v_mov_b32_e32 v12, v33
	s_waitcnt vmcnt(4)
	v_mov_b32_e32 v32, v34
	s_waitcnt vmcnt(3)
	v_mov_b32_e32 v33, v14
	v_mov_b32_e32 v14, v35
	v_mov_b32_e32 v34, v36
	v_mov_b32_e32 v35, v16
	v_mov_b32_e32 v16, v37
	v_mov_b32_e32 v5, v8
	s_waitcnt vmcnt(2)
	v_mov_b32_e32 v8, v44
	s_waitcnt vmcnt(1)
	v_mov_b32_e32 v9, v18
	v_mov_b32_e32 v18, v45
	v_mov_b32_e32 v36, v46
	v_mov_b32_e32 v37, v20
	v_mov_b32_e32 v20, v47
	v_mov_b32_e32 v38, v2
	v_mov_b32_e32 v39, v6
	v_mov_b32_e32 v6, v3
	s_waitcnt vmcnt(0)
	v_pk_mov_b32 v[2:3], v[22:23], v[22:23] op_sel:[1,0]
	v_mov_b32_e32 v25, 0
	v_permlane32_swap_b32 v8, v18
	v_permlane32_swap_b32 v9, v19
	v_permlane32_swap_b32 v36, v20
	v_permlane32_swap_b32 v37, v21
	v_permlane32_swap_b32 v38, v6
	v_permlane32_swap_b32 v39, v7
	v_permlane32_swap_b32 v4, v26
	v_permlane32_swap_b32 v5, v27
	v_permlane32_swap_b32 v28, v10
	v_permlane32_swap_b32 v29, v11
	v_permlane32_swap_b32 v30, v12
	v_permlane32_swap_b32 v31, v13
	v_permlane32_swap_b32 v32, v14
	v_permlane32_swap_b32 v33, v15
	v_permlane32_swap_b32 v34, v16
	v_permlane32_swap_b32 v35, v17
	v_bfe_u32 v128, v172, 2, 1
	v_bfe_u32 v129, v172, 3, 2
	v_and_b32_e32 v130, 3, v172
	v_lshlrev_b32_e32 v128, 4, v128
	v_lshl_add_u32 v128, v129, 2, v128
	v_add_u32_e32 v128, v128, v130
	v_mul_u32_u24_e32 v128, 0x110, v128
	v_lshrrev_b32_e32 v129, 5, v172
	v_lshl_add_u32 v126, v129, 2, v128
	v_add_u32_e32 v127, v42, v126
	ds_read2_b32 v[118:119], v127 offset0:0 offset1:2
	ds_read2_b32 v[120:121], v127 offset0:4 offset1:6
	ds_read2_b32 v[122:123], v127 offset0:8 offset1:10
	ds_read2_b32 v[124:125], v127 offset0:12 offset1:14
	s_waitcnt lgkmcnt(0)
	v_mfma_f32_32x32x2_f32 v[184:199], v118, v8, 0
	v_mfma_f32_32x32x2_f32 v[200:215], v118, v9, 0
	v_mfma_f32_32x32x2_f32 v[216:231], v118, v18, 0
	v_mfma_f32_32x32x2_f32 v[232:247], v118, v19, 0
	v_mfma_f32_32x32x2_f32 v[184:199], v119, v36, v[184:199]
	v_mfma_f32_32x32x2_f32 v[200:215], v119, v37, v[200:215]
	v_mfma_f32_32x32x2_f32 v[216:231], v119, v20, v[216:231]
	v_mfma_f32_32x32x2_f32 v[232:247], v119, v21, v[232:247]
	v_mfma_f32_32x32x2_f32 v[184:199], v120, v38, v[184:199]
	v_mfma_f32_32x32x2_f32 v[200:215], v120, v39, v[200:215]
	v_mfma_f32_32x32x2_f32 v[216:231], v120, v6, v[216:231]
	v_mfma_f32_32x32x2_f32 v[232:247], v120, v7, v[232:247]
	v_mfma_f32_32x32x2_f32 v[184:199], v121, v4, v[184:199]
	v_mfma_f32_32x32x2_f32 v[200:215], v121, v5, v[200:215]
	v_mfma_f32_32x32x2_f32 v[216:231], v121, v26, v[216:231]
	v_mfma_f32_32x32x2_f32 v[232:247], v121, v27, v[232:247]
	v_mfma_f32_32x32x2_f32 v[184:199], v122, v28, v[184:199]
	v_mfma_f32_32x32x2_f32 v[200:215], v122, v29, v[200:215]
	v_mfma_f32_32x32x2_f32 v[216:231], v122, v10, v[216:231]
	v_mfma_f32_32x32x2_f32 v[232:247], v122, v11, v[232:247]
	v_mfma_f32_32x32x2_f32 v[184:199], v123, v30, v[184:199]
	v_mfma_f32_32x32x2_f32 v[200:215], v123, v31, v[200:215]
	v_mfma_f32_32x32x2_f32 v[216:231], v123, v12, v[216:231]
	v_mfma_f32_32x32x2_f32 v[232:247], v123, v13, v[232:247]
	v_mfma_f32_32x32x2_f32 v[184:199], v124, v32, v[184:199]
	v_mfma_f32_32x32x2_f32 v[200:215], v124, v33, v[200:215]
	v_mfma_f32_32x32x2_f32 v[216:231], v124, v14, v[216:231]
	v_mfma_f32_32x32x2_f32 v[232:247], v124, v15, v[232:247]
	v_mfma_f32_32x32x2_f32 v[184:199], v125, v34, v[184:199]
	v_mfma_f32_32x32x2_f32 v[200:215], v125, v35, v[200:215]
	v_mfma_f32_32x32x2_f32 v[216:231], v125, v16, v[216:231]
	v_mfma_f32_32x32x2_f32 v[232:247], v125, v17, v[232:247]
	s_nop 18
	v_permlane32_swap_b32 v184, v216
	s_nop 18
	v_permlane32_swap_b32 v200, v232
	s_nop 16
	v_permlane32_swap_b32 v185, v217
	s_nop 16
	v_permlane32_swap_b32 v201, v233
	s_nop 14
	v_permlane32_swap_b32 v186, v218
	s_nop 14
	v_permlane32_swap_b32 v202, v234
	s_nop 12
	v_permlane32_swap_b32 v187, v219
	s_nop 12
	v_permlane32_swap_b32 v203, v235
	s_nop 10
	v_permlane32_swap_b32 v188, v220
	s_nop 10
	v_permlane32_swap_b32 v204, v236
	s_nop 8
	v_permlane32_swap_b32 v189, v221
	s_nop 8
	v_permlane32_swap_b32 v205, v237
	s_nop 6
	v_permlane32_swap_b32 v190, v222
	s_nop 6
	v_permlane32_swap_b32 v206, v238
	s_nop 4
	v_permlane32_swap_b32 v191, v223
	s_nop 4
	v_permlane32_swap_b32 v207, v239
	s_nop 2
	v_permlane32_swap_b32 v192, v224
	s_nop 2
	v_permlane32_swap_b32 v208, v240
	s_nop 0
	v_permlane32_swap_b32 v193, v225
	s_nop 0
	v_permlane32_swap_b32 v209, v241
	v_permlane32_swap_b32 v194, v226
	v_permlane32_swap_b32 v210, v242
	v_permlane32_swap_b32 v195, v227
	v_permlane32_swap_b32 v211, v243
	v_permlane32_swap_b32 v196, v228
	v_permlane32_swap_b32 v212, v244
	v_permlane32_swap_b32 v197, v229
	v_permlane32_swap_b32 v213, v245
	v_permlane32_swap_b32 v198, v230
	v_permlane32_swap_b32 v214, v246
	v_permlane32_swap_b32 v199, v231
	v_permlane32_swap_b32 v215, v247
	v_mul_f32_e32 v128, v23, v25
	v_mul_f32_e32 v129, v22, v25
	v_fma_f32 v130, v22, v24, -v128
	v_fma_f32 v131, v23, v24, v129
	v_add_f32_e32 v24, v130, v184
	v_add_f32_e32 v25, v131, v200
	v_mul_f32_e32 v128, v23, v25
	v_mul_f32_e32 v129, v22, v25
	v_fma_f32 v130, v22, v24, -v128
	v_fma_f32 v131, v23, v24, v129
	v_add_f32_e32 v24, v130, v185
	v_add_f32_e32 v25, v131, v201
	v_mul_f32_e32 v128, v23, v25
	v_mul_f32_e32 v129, v22, v25
	v_fma_f32 v130, v22, v24, -v128
	v_fma_f32 v131, v23, v24, v129
	v_add_f32_e32 v24, v130, v186
	v_add_f32_e32 v25, v131, v202
	v_mul_f32_e32 v128, v23, v25
	v_mul_f32_e32 v129, v22, v25
	v_fma_f32 v130, v22, v24, -v128
	v_fma_f32 v131, v23, v24, v129
	v_add_f32_e32 v24, v130, v187
	v_add_f32_e32 v25, v131, v203
	v_mul_f32_e32 v128, v23, v25
	v_mul_f32_e32 v129, v22, v25
	v_fma_f32 v130, v22, v24, -v128
	v_fma_f32 v131, v23, v24, v129
	v_add_f32_e32 v24, v130, v188
	v_add_f32_e32 v25, v131, v204
	v_mul_f32_e32 v128, v23, v25
	v_mul_f32_e32 v129, v22, v25
	v_fma_f32 v130, v22, v24, -v128
	v_fma_f32 v131, v23, v24, v129
	v_add_f32_e32 v24, v130, v189
	v_add_f32_e32 v25, v131, v205
	v_mul_f32_e32 v128, v23, v25
	v_mul_f32_e32 v129, v22, v25
	v_fma_f32 v130, v22, v24, -v128
	v_fma_f32 v131, v23, v24, v129
	v_add_f32_e32 v24, v130, v190
	v_add_f32_e32 v25, v131, v206
	v_mul_f32_e32 v128, v23, v25
	v_mul_f32_e32 v129, v22, v25
	v_fma_f32 v130, v22, v24, -v128
	v_fma_f32 v131, v23, v24, v129
	v_add_f32_e32 v24, v130, v191
	v_add_f32_e32 v25, v131, v207
	v_mul_f32_e32 v128, v23, v25
	v_mul_f32_e32 v129, v22, v25
	v_fma_f32 v130, v22, v24, -v128
	v_fma_f32 v131, v23, v24, v129
	v_add_f32_e32 v24, v130, v192
	v_add_f32_e32 v25, v131, v208
	v_mul_f32_e32 v128, v23, v25
	v_mul_f32_e32 v129, v22, v25
	v_fma_f32 v130, v22, v24, -v128
	v_fma_f32 v131, v23, v24, v129
	v_add_f32_e32 v24, v130, v193
	v_add_f32_e32 v25, v131, v209
	v_mul_f32_e32 v128, v23, v25
	v_mul_f32_e32 v129, v22, v25
	v_fma_f32 v130, v22, v24, -v128
	v_fma_f32 v131, v23, v24, v129
	v_add_f32_e32 v24, v130, v194
	v_add_f32_e32 v25, v131, v210
	v_mul_f32_e32 v128, v23, v25
	v_mul_f32_e32 v129, v22, v25
	v_fma_f32 v130, v22, v24, -v128
	v_fma_f32 v131, v23, v24, v129
	v_add_f32_e32 v24, v130, v195
	v_add_f32_e32 v25, v131, v211
	v_mul_f32_e32 v128, v23, v25
	v_mul_f32_e32 v129, v22, v25
	v_fma_f32 v130, v22, v24, -v128
	v_fma_f32 v131, v23, v24, v129
	v_add_f32_e32 v24, v130, v196
	v_add_f32_e32 v25, v131, v212
	v_mul_f32_e32 v128, v23, v25
	v_mul_f32_e32 v129, v22, v25
	v_fma_f32 v130, v22, v24, -v128
	v_fma_f32 v131, v23, v24, v129
	v_add_f32_e32 v24, v130, v197
	v_add_f32_e32 v25, v131, v213
	v_mul_f32_e32 v128, v23, v25
	v_mul_f32_e32 v129, v22, v25
	v_fma_f32 v130, v22, v24, -v128
	v_fma_f32 v131, v23, v24, v129
	v_add_f32_e32 v24, v130, v198
	v_add_f32_e32 v25, v131, v214
	v_mul_f32_e32 v128, v23, v25
	v_mul_f32_e32 v129, v22, v25
	v_fma_f32 v130, v22, v24, -v128
	v_fma_f32 v131, v23, v24, v129
	v_add_f32_e32 v24, v130, v199
	v_add_f32_e32 v25, v131, v215
	v_mul_f32_e32 v128, v23, v25
	v_mul_f32_e32 v129, v22, v25
	v_fma_f32 v130, v22, v24, -v128
	v_fma_f32 v131, v23, v24, v129
	v_add_f32_e32 v24, v130, v216
	v_add_f32_e32 v25, v131, v232
	v_mul_f32_e32 v128, v23, v25
	v_mul_f32_e32 v129, v22, v25
	v_fma_f32 v130, v22, v24, -v128
	v_fma_f32 v131, v23, v24, v129
	v_add_f32_e32 v24, v130, v217
	v_add_f32_e32 v25, v131, v233
	v_mul_f32_e32 v128, v23, v25
	v_mul_f32_e32 v129, v22, v25
	v_fma_f32 v130, v22, v24, -v128
	v_fma_f32 v131, v23, v24, v129
	v_add_f32_e32 v24, v130, v218
	v_add_f32_e32 v25, v131, v234
	v_mul_f32_e32 v128, v23, v25
	v_mul_f32_e32 v129, v22, v25
	v_fma_f32 v130, v22, v24, -v128
	v_fma_f32 v131, v23, v24, v129
	v_add_f32_e32 v24, v130, v219
	v_add_f32_e32 v25, v131, v235
	v_mul_f32_e32 v128, v23, v25
	v_mul_f32_e32 v129, v22, v25
	v_fma_f32 v130, v22, v24, -v128
	v_fma_f32 v131, v23, v24, v129
	v_add_f32_e32 v24, v130, v220
	v_add_f32_e32 v25, v131, v236
	v_mul_f32_e32 v128, v23, v25
	v_mul_f32_e32 v129, v22, v25
	v_fma_f32 v130, v22, v24, -v128
	v_fma_f32 v131, v23, v24, v129
	v_add_f32_e32 v24, v130, v221
	v_add_f32_e32 v25, v131, v237
	v_mul_f32_e32 v128, v23, v25
	v_mul_f32_e32 v129, v22, v25
	v_fma_f32 v130, v22, v24, -v128
	v_fma_f32 v131, v23, v24, v129
	v_add_f32_e32 v24, v130, v222
	v_add_f32_e32 v25, v131, v238
	v_mul_f32_e32 v128, v23, v25
	v_mul_f32_e32 v129, v22, v25
	v_fma_f32 v130, v22, v24, -v128
	v_fma_f32 v131, v23, v24, v129
	v_add_f32_e32 v24, v130, v223
	v_add_f32_e32 v25, v131, v239
	v_mul_f32_e32 v128, v23, v25
	v_mul_f32_e32 v129, v22, v25
	v_fma_f32 v130, v22, v24, -v128
	v_fma_f32 v131, v23, v24, v129
	v_add_f32_e32 v24, v130, v224
	v_add_f32_e32 v25, v131, v240
	v_mul_f32_e32 v128, v23, v25
	v_mul_f32_e32 v129, v22, v25
	v_fma_f32 v130, v22, v24, -v128
	v_fma_f32 v131, v23, v24, v129
	v_add_f32_e32 v24, v130, v225
	v_add_f32_e32 v25, v131, v241
	v_mul_f32_e32 v128, v23, v25
	v_mul_f32_e32 v129, v22, v25
	v_fma_f32 v130, v22, v24, -v128
	v_fma_f32 v131, v23, v24, v129
	v_add_f32_e32 v24, v130, v226
	v_add_f32_e32 v25, v131, v242
	v_mul_f32_e32 v128, v23, v25
	v_mul_f32_e32 v129, v22, v25
	v_fma_f32 v130, v22, v24, -v128
	v_fma_f32 v131, v23, v24, v129
	v_add_f32_e32 v24, v130, v227
	v_add_f32_e32 v25, v131, v243
	v_mul_f32_e32 v128, v23, v25
	v_mul_f32_e32 v129, v22, v25
	v_fma_f32 v130, v22, v24, -v128
	v_fma_f32 v131, v23, v24, v129
	v_add_f32_e32 v24, v130, v228
	v_add_f32_e32 v25, v131, v244
	v_mul_f32_e32 v128, v23, v25
	v_mul_f32_e32 v129, v22, v25
	v_fma_f32 v130, v22, v24, -v128
	v_fma_f32 v131, v23, v24, v129
	v_add_f32_e32 v24, v130, v229
	v_add_f32_e32 v25, v131, v245
	v_mul_f32_e32 v128, v23, v25
	v_mul_f32_e32 v129, v22, v25
	v_fma_f32 v130, v22, v24, -v128
	v_fma_f32 v131, v23, v24, v129
	v_add_f32_e32 v24, v130, v230
	v_add_f32_e32 v25, v131, v246
	v_mul_f32_e32 v128, v23, v25
	v_mul_f32_e32 v129, v22, v25
	v_fma_f32 v130, v22, v24, -v128
	v_fma_f32 v131, v23, v24, v129
	v_add_f32_e32 v24, v130, v231
	v_add_f32_e32 v25, v131, v247
	v_add_u32_e32 v127, 0x2200, v127
	ds_read2_b32 v[118:119], v127 offset0:0 offset1:2
	ds_read2_b32 v[120:121], v127 offset0:4 offset1:6
	ds_read2_b32 v[122:123], v127 offset0:8 offset1:10
	ds_read2_b32 v[124:125], v127 offset0:12 offset1:14
	s_waitcnt lgkmcnt(0)
	v_mfma_f32_32x32x2_f32 v[184:199], v118, v8, 0
	v_mfma_f32_32x32x2_f32 v[200:215], v118, v9, 0
	v_mfma_f32_32x32x2_f32 v[216:231], v118, v18, 0
	v_mfma_f32_32x32x2_f32 v[232:247], v118, v19, 0
	v_mfma_f32_32x32x2_f32 v[184:199], v119, v36, v[184:199]
	v_mfma_f32_32x32x2_f32 v[200:215], v119, v37, v[200:215]
	v_mfma_f32_32x32x2_f32 v[216:231], v119, v20, v[216:231]
	v_mfma_f32_32x32x2_f32 v[232:247], v119, v21, v[232:247]
	v_mfma_f32_32x32x2_f32 v[184:199], v120, v38, v[184:199]
	v_mfma_f32_32x32x2_f32 v[200:215], v120, v39, v[200:215]
	v_mfma_f32_32x32x2_f32 v[216:231], v120, v6, v[216:231]
	v_mfma_f32_32x32x2_f32 v[232:247], v120, v7, v[232:247]
	v_mfma_f32_32x32x2_f32 v[184:199], v121, v4, v[184:199]
	v_mfma_f32_32x32x2_f32 v[200:215], v121, v5, v[200:215]
	v_mfma_f32_32x32x2_f32 v[216:231], v121, v26, v[216:231]
	v_mfma_f32_32x32x2_f32 v[232:247], v121, v27, v[232:247]
	v_mfma_f32_32x32x2_f32 v[184:199], v122, v28, v[184:199]
	v_mfma_f32_32x32x2_f32 v[200:215], v122, v29, v[200:215]
	v_mfma_f32_32x32x2_f32 v[216:231], v122, v10, v[216:231]
	v_mfma_f32_32x32x2_f32 v[232:247], v122, v11, v[232:247]
	v_mfma_f32_32x32x2_f32 v[184:199], v123, v30, v[184:199]
	v_mfma_f32_32x32x2_f32 v[200:215], v123, v31, v[200:215]
	v_mfma_f32_32x32x2_f32 v[216:231], v123, v12, v[216:231]
	v_mfma_f32_32x32x2_f32 v[232:247], v123, v13, v[232:247]
	v_mfma_f32_32x32x2_f32 v[184:199], v124, v32, v[184:199]
	v_mfma_f32_32x32x2_f32 v[200:215], v124, v33, v[200:215]
	v_mfma_f32_32x32x2_f32 v[216:231], v124, v14, v[216:231]
	v_mfma_f32_32x32x2_f32 v[232:247], v124, v15, v[232:247]
	v_mfma_f32_32x32x2_f32 v[184:199], v125, v34, v[184:199]
	v_mfma_f32_32x32x2_f32 v[200:215], v125, v35, v[200:215]
	v_mfma_f32_32x32x2_f32 v[216:231], v125, v16, v[216:231]
	v_mfma_f32_32x32x2_f32 v[232:247], v125, v17, v[232:247]
	s_nop 18
	v_permlane32_swap_b32 v184, v216
	s_nop 18
	v_permlane32_swap_b32 v200, v232
	s_nop 16
	v_permlane32_swap_b32 v185, v217
	s_nop 16
	v_permlane32_swap_b32 v201, v233
	s_nop 14
	v_permlane32_swap_b32 v186, v218
	s_nop 14
	v_permlane32_swap_b32 v202, v234
	s_nop 12
	v_permlane32_swap_b32 v187, v219
	s_nop 12
	v_permlane32_swap_b32 v203, v235
	s_nop 10
	v_permlane32_swap_b32 v188, v220
	s_nop 10
	v_permlane32_swap_b32 v204, v236
	s_nop 8
	v_permlane32_swap_b32 v189, v221
	s_nop 8
	v_permlane32_swap_b32 v205, v237
	s_nop 6
	v_permlane32_swap_b32 v190, v222
	s_nop 6
	v_permlane32_swap_b32 v206, v238
	s_nop 4
	v_permlane32_swap_b32 v191, v223
	s_nop 4
	v_permlane32_swap_b32 v207, v239
	s_nop 2
	v_permlane32_swap_b32 v192, v224
	s_nop 2
	v_permlane32_swap_b32 v208, v240
	s_nop 0
	v_permlane32_swap_b32 v193, v225
	s_nop 0
	v_permlane32_swap_b32 v209, v241
	v_permlane32_swap_b32 v194, v226
	v_permlane32_swap_b32 v210, v242
	v_permlane32_swap_b32 v195, v227
	v_permlane32_swap_b32 v211, v243
	v_permlane32_swap_b32 v196, v228
	v_permlane32_swap_b32 v212, v244
	v_permlane32_swap_b32 v197, v229
	v_permlane32_swap_b32 v213, v245
	v_permlane32_swap_b32 v198, v230
	v_permlane32_swap_b32 v214, v246
	v_permlane32_swap_b32 v199, v231
	v_permlane32_swap_b32 v215, v247
	v_mul_f32_e32 v128, v23, v25
	v_mul_f32_e32 v129, v22, v25
	v_fma_f32 v130, v22, v24, -v128
	v_fma_f32 v131, v23, v24, v129
	v_add_f32_e32 v24, v130, v184
	v_add_f32_e32 v25, v131, v200
	v_mul_f32_e32 v128, v23, v25
	v_mul_f32_e32 v129, v22, v25
	v_fma_f32 v130, v22, v24, -v128
	v_fma_f32 v131, v23, v24, v129
	v_add_f32_e32 v24, v130, v185
	v_add_f32_e32 v25, v131, v201
	v_mul_f32_e32 v128, v23, v25
	v_mul_f32_e32 v129, v22, v25
	v_fma_f32 v130, v22, v24, -v128
	v_fma_f32 v131, v23, v24, v129
	v_add_f32_e32 v24, v130, v186
	v_add_f32_e32 v25, v131, v202
	v_mul_f32_e32 v128, v23, v25
	v_mul_f32_e32 v129, v22, v25
	v_fma_f32 v130, v22, v24, -v128
	v_fma_f32 v131, v23, v24, v129
	v_add_f32_e32 v24, v130, v187
	v_add_f32_e32 v25, v131, v203
	v_mul_f32_e32 v128, v23, v25
	v_mul_f32_e32 v129, v22, v25
	v_fma_f32 v130, v22, v24, -v128
	v_fma_f32 v131, v23, v24, v129
	v_add_f32_e32 v24, v130, v188
	v_add_f32_e32 v25, v131, v204
	v_mul_f32_e32 v128, v23, v25
	v_mul_f32_e32 v129, v22, v25
	v_fma_f32 v130, v22, v24, -v128
	v_fma_f32 v131, v23, v24, v129
	v_add_f32_e32 v24, v130, v189
	v_add_f32_e32 v25, v131, v205
	v_mul_f32_e32 v128, v23, v25
	v_mul_f32_e32 v129, v22, v25
	v_fma_f32 v130, v22, v24, -v128
	v_fma_f32 v131, v23, v24, v129
	v_add_f32_e32 v24, v130, v190
	v_add_f32_e32 v25, v131, v206
	v_mul_f32_e32 v128, v23, v25
	v_mul_f32_e32 v129, v22, v25
	v_fma_f32 v130, v22, v24, -v128
	v_fma_f32 v131, v23, v24, v129
	v_add_f32_e32 v24, v130, v191
	v_add_f32_e32 v25, v131, v207
	v_mul_f32_e32 v128, v23, v25
	v_mul_f32_e32 v129, v22, v25
	v_fma_f32 v130, v22, v24, -v128
	v_fma_f32 v131, v23, v24, v129
	v_add_f32_e32 v24, v130, v192
	v_add_f32_e32 v25, v131, v208
	v_mul_f32_e32 v128, v23, v25
	v_mul_f32_e32 v129, v22, v25
	v_fma_f32 v130, v22, v24, -v128
	v_fma_f32 v131, v23, v24, v129
	v_add_f32_e32 v24, v130, v193
	v_add_f32_e32 v25, v131, v209
	v_mul_f32_e32 v128, v23, v25
	v_mul_f32_e32 v129, v22, v25
	v_fma_f32 v130, v22, v24, -v128
	v_fma_f32 v131, v23, v24, v129
	v_add_f32_e32 v24, v130, v194
	v_add_f32_e32 v25, v131, v210
	v_mul_f32_e32 v128, v23, v25
	v_mul_f32_e32 v129, v22, v25
	v_fma_f32 v130, v22, v24, -v128
	v_fma_f32 v131, v23, v24, v129
	v_add_f32_e32 v24, v130, v195
	v_add_f32_e32 v25, v131, v211
	v_mul_f32_e32 v128, v23, v25
	v_mul_f32_e32 v129, v22, v25
	v_fma_f32 v130, v22, v24, -v128
	v_fma_f32 v131, v23, v24, v129
	v_add_f32_e32 v24, v130, v196
	v_add_f32_e32 v25, v131, v212
	v_mul_f32_e32 v128, v23, v25
	v_mul_f32_e32 v129, v22, v25
	v_fma_f32 v130, v22, v24, -v128
	v_fma_f32 v131, v23, v24, v129
	v_add_f32_e32 v24, v130, v197
	v_add_f32_e32 v25, v131, v213
	v_mul_f32_e32 v128, v23, v25
	v_mul_f32_e32 v129, v22, v25
; DI int tidx() { int t = threadIdx.x & 255; asm volatile("" : "+v"(t)); return t; }
; DI void ssm1_item(PREF p, int l, int item, unsigned char* ldsb) {
;   const int gq = item & 3, c = (item >> 2) & 63, b = item >> 8;
;   const int tid = tidx(), w = tid >> 6, lane = tid & 63;
;   const int g = gq * 4 + w;
;   float* uS = (float*)ldsb;
;   __syncthreads();
;   ssm_stage_u(p, b, c, gq, uS);
;   __syncthreads();
;   const size_t pi = (size_t)(l * 16 + g) * 64 + lane;
;   float bre[16], bim[16];
; #pragma unroll
;   for (int j = 0; j < 16; ++j) { bre[j] = p.bbre[pi * 16 + j]; bim[j] = p.bbim[pi * 16 + j]; }
;   const float lr = p.lam[pi * 2], li = p.lam[pi * 2 + 1];
;   float hr = 0.f, hi = 0.f;
;   for (int t = 0; t < 64; ++t) SSM_STEP(t)
;   ((float2*)p.hend)[((size_t)(b * 16 + g) * 64 + c) * 64 + lane] = make_float2(hr, hi);
	v_fma_f32 v130, v22, v24, -v128
	v_fma_f32 v131, v23, v24, v129
	v_add_f32_e32 v24, v130, v198
	v_add_f32_e32 v25, v131, v214
	v_mul_f32_e32 v128, v23, v25
	v_mul_f32_e32 v129, v22, v25
	v_fma_f32 v130, v22, v24, -v128
	v_fma_f32 v131, v23, v24, v129
	v_add_f32_e32 v24, v130, v199
	v_add_f32_e32 v25, v131, v215
	v_mul_f32_e32 v128, v23, v25
	v_mul_f32_e32 v129, v22, v25
	v_fma_f32 v130, v22, v24, -v128
	v_fma_f32 v131, v23, v24, v129
	v_add_f32_e32 v24, v130, v216
	v_add_f32_e32 v25, v131, v232
	v_mul_f32_e32 v128, v23, v25
	v_mul_f32_e32 v129, v22, v25
	v_fma_f32 v130, v22, v24, -v128
	v_fma_f32 v131, v23, v24, v129
	v_add_f32_e32 v24, v130, v217
	v_add_f32_e32 v25, v131, v233
	v_mul_f32_e32 v128, v23, v25
	v_mul_f32_e32 v129, v22, v25
	v_fma_f32 v130, v22, v24, -v128
	v_fma_f32 v131, v23, v24, v129
	v_add_f32_e32 v24, v130, v218
	v_add_f32_e32 v25, v131, v234
	v_mul_f32_e32 v128, v23, v25
	v_mul_f32_e32 v129, v22, v25
	v_fma_f32 v130, v22, v24, -v128
	v_fma_f32 v131, v23, v24, v129
	v_add_f32_e32 v24, v130, v219
	v_add_f32_e32 v25, v131, v235
	v_mul_f32_e32 v128, v23, v25
	v_mul_f32_e32 v129, v22, v25
	v_fma_f32 v130, v22, v24, -v128
	v_fma_f32 v131, v23, v24, v129
	v_add_f32_e32 v24, v130, v220
	v_add_f32_e32 v25, v131, v236
	v_mul_f32_e32 v128, v23, v25
	v_mul_f32_e32 v129, v22, v25
	v_fma_f32 v130, v22, v24, -v128
	v_fma_f32 v131, v23, v24, v129
	v_add_f32_e32 v24, v130, v221
	v_add_f32_e32 v25, v131, v237
	v_mul_f32_e32 v128, v23, v25
	v_mul_f32_e32 v129, v22, v25
	v_fma_f32 v130, v22, v24, -v128
	v_fma_f32 v131, v23, v24, v129
	v_add_f32_e32 v24, v130, v222
	v_add_f32_e32 v25, v131, v238
	v_mul_f32_e32 v128, v23, v25
	v_mul_f32_e32 v129, v22, v25
	v_fma_f32 v130, v22, v24, -v128
	v_fma_f32 v131, v23, v24, v129
	v_add_f32_e32 v24, v130, v223
	v_add_f32_e32 v25, v131, v239
	v_mul_f32_e32 v128, v23, v25
	v_mul_f32_e32 v129, v22, v25
	v_fma_f32 v130, v22, v24, -v128
	v_fma_f32 v131, v23, v24, v129
	v_add_f32_e32 v24, v130, v224
	v_add_f32_e32 v25, v131, v240
	v_mul_f32_e32 v128, v23, v25
	v_mul_f32_e32 v129, v22, v25
	v_fma_f32 v130, v22, v24, -v128
	v_fma_f32 v131, v23, v24, v129
	v_add_f32_e32 v24, v130, v225
	v_add_f32_e32 v25, v131, v241
	v_mul_f32_e32 v128, v23, v25
	v_mul_f32_e32 v129, v22, v25
	v_fma_f32 v130, v22, v24, -v128
	v_fma_f32 v131, v23, v24, v129
	v_add_f32_e32 v24, v130, v226
	v_add_f32_e32 v25, v131, v242
	v_mul_f32_e32 v128, v23, v25
	v_mul_f32_e32 v129, v22, v25
	v_fma_f32 v130, v22, v24, -v128
	v_fma_f32 v131, v23, v24, v129
	v_add_f32_e32 v24, v130, v227
	v_add_f32_e32 v25, v131, v243
	v_mul_f32_e32 v128, v23, v25
	v_mul_f32_e32 v129, v22, v25
	v_fma_f32 v130, v22, v24, -v128
	v_fma_f32 v131, v23, v24, v129
	v_add_f32_e32 v24, v130, v228
	v_add_f32_e32 v25, v131, v244
	v_mul_f32_e32 v128, v23, v25
	v_mul_f32_e32 v129, v22, v25
	v_fma_f32 v130, v22, v24, -v128
	v_fma_f32 v131, v23, v24, v129
	v_add_f32_e32 v24, v130, v229
	v_add_f32_e32 v25, v131, v245
	v_mul_f32_e32 v128, v23, v25
	v_mul_f32_e32 v129, v22, v25
	v_fma_f32 v130, v22, v24, -v128
	v_fma_f32 v131, v23, v24, v129
	v_add_f32_e32 v24, v130, v230
	v_add_f32_e32 v25, v131, v246
	v_mul_f32_e32 v128, v23, v25
	v_mul_f32_e32 v129, v22, v25
	v_fma_f32 v130, v22, v24, -v128
	v_fma_f32 v131, v23, v24, v129
	v_add_f32_e32 v24, v130, v231
	v_add_f32_e32 v25, v131, v247
	v_readlane_b32 s18, v254, 46
	v_readlane_b32 s19, v254, 47
	s_load_dwordx2 s[0:1], s[18:19], 0x188
	v_lshl_add_u32 v2, s14, 4, v41
	v_ashrrev_i32_e32 v3, 31, v2
	v_lshlrev_b64 v[2:3], 15, v[2:3]
	s_lshl_b32 s52, s15, 3
	s_waitcnt lgkmcnt(0)
	v_lshl_add_u64 v[2:3], s[0:1], 0, v[2:3]
	v_lshl_add_u64 v[2:3], v[2:3], 0, s[52:53]
	v_lshlrev_b32_e32 v0, 3, v0
	s_add_i32 s12, s12, s71
	v_lshl_add_u64 v[2:3], v[2:3], 0, v[0:1]
	s_cmpk_gt_i32 s12, 0x7ff
	global_store_dwordx2 v[2:3], v[24:25], off
	s_cbranch_scc0 .LBB0_422
